# prologue weight transposes: 16 LDS read-backs per item issued back to back with counted waits instead of read-wait-convert round trips
# baseline (speedup 1.0000x reference)
.LBB0_15:
	s_mul_hi_i32 s10, s35, 0xb21642c9
	s_add_i32 s10, s10, s35
	s_lshr_b32 s11, s10, 31
	s_ashr_i32 s10, s10, 14
	s_add_i32 s10, s10, s11
	s_mul_i32 s11, s10, 0xffffa400
	s_add_i32 s11, s35, s11
	s_cmpk_gt_i32 s11, 0xfff
	s_mov_b64 s[26:27], -1
	s_cbranch_scc0 .LBB0_25
	s_cmpk_gt_u32 s11, 0x19ff
	s_cbranch_scc0 .LBB0_22
	s_cmpk_gt_u32 s11, 0x45ff
	s_mul_hi_i32 s36, s10, 0x2c00000
	s_mul_i32 s37, s10, 0x2c00000
	s_cbranch_scc0 .LBB0_19
	s_load_dwordx2 s[26:27], s[22:23], 0xa0
	s_and_b32 s12, s11, 0x7fffffc0
	s_addk_i32 s12, 0xba00
	s_mul_hi_i32 s13, s10, 0x1600000
	v_or_b32_e32 v56, s12, v6
	s_waitcnt lgkmcnt(0)
	s_add_u32 s24, s26, s37
	s_addc_u32 s27, s27, s36
	s_and_b32 s38, s33, 0x7e0
	s_mul_i32 s26, s10, 0x1600000
	s_add_u32 s39, s6, s26
	s_addc_u32 s13, s7, s13
	s_lshl_b32 s26, s38, 2
	s_add_u32 s26, s24, s26
	s_addc_u32 s27, s27, 0
	v_mov_b32_e32 v57, v3
	v_or_b32_e32 v30, 8, v56
	v_mov_b32_e32 v31, v3
	v_or_b32_e32 v36, 16, v56
	v_mov_b32_e32 v37, v3
	v_or_b32_e32 v38, 24, v56
	v_mov_b32_e32 v39, v3
	v_or_b32_e32 v44, 32, v56
	v_mov_b32_e32 v45, v3
	v_or_b32_e32 v46, 40, v56
	v_mov_b32_e32 v47, v3
	v_lshl_add_u64 v[58:59], s[26:27], 0, v[2:3]
	v_lshlrev_b64 v[28:29], 13, v[56:57]
	v_lshlrev_b64 v[30:31], 13, v[30:31]
	v_lshlrev_b64 v[36:37], 13, v[36:37]
	v_lshlrev_b64 v[38:39], 13, v[38:39]
	v_lshlrev_b64 v[44:45], 13, v[44:45]
	v_lshlrev_b64 v[46:47], 13, v[46:47]
	v_lshl_add_u64 v[28:29], v[58:59], 0, v[28:29]
	v_lshl_add_u64 v[32:33], v[58:59], 0, v[30:31]
	v_lshl_add_u64 v[36:37], v[58:59], 0, v[36:37]
	v_lshl_add_u64 v[40:41], v[58:59], 0, v[38:39]
	v_lshl_add_u64 v[44:45], v[58:59], 0, v[44:45]
	v_lshl_add_u64 v[48:49], v[58:59], 0, v[46:47]
	global_load_dwordx4 v[28:31], v[28:29], off
	s_nop 0
	global_load_dwordx4 v[32:35], v[32:33], off
	s_nop 0
	global_load_dwordx4 v[36:39], v[36:37], off
	s_nop 0
	global_load_dwordx4 v[40:43], v[40:41], off
	s_nop 0
	global_load_dwordx4 v[44:47], v[44:45], off
	s_nop 0
	global_load_dwordx4 v[48:51], v[48:49], off
	v_or_b32_e32 v52, 48, v56
	v_mov_b32_e32 v53, v3
	v_lshlrev_b64 v[52:53], 13, v[52:53]
	v_lshl_add_u64 v[52:53], v[58:59], 0, v[52:53]
	v_or_b32_e32 v56, 56, v56
	global_load_dwordx4 v[52:55], v[52:53], off
	v_lshlrev_b64 v[56:57], 13, v[56:57]
	v_lshl_add_u64 v[56:57], v[58:59], 0, v[56:57]
	global_load_dwordx4 v[56:59], v[56:57], off
	s_bfe_u32 s24, s33, 0x30008
	s_lshr_b32 s12, s12, 6
	s_mulk_i32 s24, 0x58
	s_add_i32 s24, s24, s12
	s_lshl_b64 s[26:27], s[24:25], 15
	s_add_u32 s26, s39, s26
	s_addc_u32 s27, s13, s27
	v_mov_b32_e32 v5, v3
	s_waitcnt vmcnt(7)
	ds_write2_b32 v12, v28, v29 offset1:1
	ds_write2_b32 v12, v30, v31 offset0:2 offset1:3
	s_waitcnt vmcnt(6)
	ds_write2_b32 v13, v32, v33 offset1:1
	ds_write2_b32 v14, v34, v35 offset1:1
	s_waitcnt vmcnt(5)
	ds_write2_b32 v15, v36, v37 offset1:1
	ds_write2_b32 v16, v38, v39 offset1:1
	s_waitcnt vmcnt(4)
	ds_write2_b32 v17, v40, v41 offset1:1
	ds_write2_b32 v18, v42, v43 offset1:1
	s_waitcnt vmcnt(3)
	ds_write2_b32 v19, v44, v45 offset1:1
	ds_write2_b32 v20, v46, v47 offset1:1
	s_waitcnt vmcnt(2)
	ds_write2_b32 v21, v48, v49 offset1:1
	ds_write2_b32 v22, v50, v51 offset1:1
	s_waitcnt vmcnt(1)
	ds_write2_b32 v23, v52, v53 offset1:1
	ds_write2_b32 v24, v54, v55 offset1:1
	s_waitcnt vmcnt(0)
	ds_write2_b32 v25, v56, v57 offset1:1
	ds_write2_b32 v27, v58, v59 offset1:1
	s_waitcnt lgkmcnt(0)
	v_or_b32_e32 v32, s38, v6
	ds_read2_b32 v[60:61], v10 offset1:33
	ds_read2_b32 v[62:63], v10 offset0:66 offset1:99
	ds_read2_b32 v[64:65], v10 offset0:132 offset1:165
	ds_read2_b32 v[66:67], v10 offset0:198 offset1:231
	ds_read2_b32 v[68:69], v10 offset0:8 offset1:41
	ds_read2_b32 v[70:71], v10 offset0:74 offset1:107
	ds_read2_b32 v[72:73], v10 offset0:140 offset1:173
	ds_read2_b32 v[74:75], v10 offset0:206 offset1:239
	ds_read2_b32 v[76:77], v10 offset0:16 offset1:49
	ds_read2_b32 v[78:79], v10 offset0:82 offset1:115
	ds_read2_b32 v[80:81], v10 offset0:148 offset1:181
	ds_read2_b32 v[82:83], v10 offset0:214 offset1:247
	ds_read2_b32 v[84:85], v10 offset0:24 offset1:57
	ds_read2_b32 v[86:87], v10 offset0:90 offset1:123
	ds_read2_b32 v[88:89], v10 offset0:156 offset1:189
	ds_read2_b32 v[90:91], v10 offset0:222 offset1:255
	v_lshlrev_b32_e32 v32, 7, v32
	s_waitcnt lgkmcnt(15)
	v_cvt_pk_bf16_f32 v28, v60, v61
	v_mov_b32_e32 v33, v3
	v_and_b32_e32 v32, 0x7380, v32
	s_waitcnt lgkmcnt(14)
	v_cvt_pk_bf16_f32 v29, v62, v63
	v_lshl_add_u64 v[32:33], s[26:27], 0, v[32:33]
	s_waitcnt lgkmcnt(13)
	v_cvt_pk_bf16_f32 v30, v64, v65
	s_waitcnt lgkmcnt(12)
	v_cvt_pk_bf16_f32 v31, v66, v67
	v_lshl_add_u64 v[32:33], v[32:33], 0, v[4:5]
	global_store_dwordx4 v[32:33], v[28:31], off
	s_waitcnt lgkmcnt(11)
	s_nop 0
	v_cvt_pk_bf16_f32 v28, v68, v69
	s_waitcnt lgkmcnt(10)
	v_cvt_pk_bf16_f32 v29, v70, v71
	s_waitcnt lgkmcnt(9)
	v_cvt_pk_bf16_f32 v30, v72, v73
	v_or_b32_e32 v31, s38, v7
	v_lshlrev_b32_e32 v34, 7, v31
	v_mov_b32_e32 v35, v3
	v_and_b32_e32 v34, 0x7780, v34
	v_lshl_add_u64 v[34:35], s[26:27], 0, v[34:35]
	s_waitcnt lgkmcnt(8)
	v_cvt_pk_bf16_f32 v31, v74, v75
	v_lshl_add_u64 v[34:35], v[34:35], 0, v[4:5]
	global_store_dwordx4 v[34:35], v[28:31], off
	v_mov_b32_e32 v35, v3
	s_waitcnt lgkmcnt(7)
	v_cvt_pk_bf16_f32 v28, v76, v77
	s_waitcnt lgkmcnt(6)
	v_cvt_pk_bf16_f32 v29, v78, v79
	s_waitcnt lgkmcnt(5)
	v_cvt_pk_bf16_f32 v30, v80, v81
	v_or_b32_e32 v31, s38, v8
	v_lshlrev_b32_e32 v34, 7, v31
	v_and_b32_e32 v34, 0x7b80, v34
	v_lshl_add_u64 v[34:35], s[26:27], 0, v[34:35]
	s_waitcnt lgkmcnt(4)
	v_cvt_pk_bf16_f32 v31, v82, v83
	v_lshl_add_u64 v[34:35], v[34:35], 0, v[4:5]
	global_store_dwordx4 v[34:35], v[28:31], off
	s_waitcnt lgkmcnt(3)
	s_nop 0
	v_cvt_pk_bf16_f32 v28, v84, v85
	s_waitcnt lgkmcnt(2)
	v_cvt_pk_bf16_f32 v29, v86, v87
	s_waitcnt lgkmcnt(1)
	v_cvt_pk_bf16_f32 v30, v88, v89
	v_or_b32_e32 v31, s38, v9
	v_lshlrev_b32_e32 v31, 7, v31
	v_mov_b32_e32 v33, v3
	v_and_b32_e32 v32, 0x7f80, v31
	v_lshl_add_u64 v[32:33], s[26:27], 0, v[32:33]
	v_lshl_add_u64 v[32:33], v[32:33], 0, v[4:5]
	s_waitcnt lgkmcnt(0)
	v_cvt_pk_bf16_f32 v31, v90, v91
	global_store_dwordx4 v[32:33], v[28:31], off
	s_waitcnt lgkmcnt(0)
	s_mov_b64 s[26:27], 0
.LBB0_19:
	s_andn2_b64 vcc, exec, s[26:27]
	s_cbranch_vccnz .LBB0_21
	s_add_i32 s12, s11, 0xe600
	s_and_b32 s13, s12, 0xffff
	s_mul_i32 s13, s13, 0xba2f
	s_lshr_b32 s13, s13, 24
	s_mul_i32 s24, s13, 0x160
	s_sub_i32 s12, s12, s24
	s_and_b32 s26, s12, 0xffff
	s_lshl_b32 s24, s26, 5
	s_bfe_i32 s27, s12, 0x10002
	s_lshl_b32 s26, s26, 4
	s_and_b32 s27, s27, 0x1600
	s_and_b32 s26, s26, 0x1f80
	s_add_i32 s38, s27, s26
	s_load_dwordx2 s[26:27], s[22:23], 0x88
	s_and_b32 s39, s24, 0x60
	s_or_b32 s38, s38, s39
	s_mul_i32 s40, s10, 0x5800000
	s_mul_hi_i32 s39, s10, 0x5800000
	s_waitcnt lgkmcnt(0)
	s_add_u32 s26, s26, s40
	s_addc_u32 s27, s27, s39
	s_add_u32 s37, s8, s37
	s_addc_u32 s36, s9, s36
	s_lshl_b32 s38, s38, 2
	v_lshl_or_b32 v5, s13, 6, v6
	s_add_u32 s26, s26, s38
	s_addc_u32 s27, s27, 0
	v_mul_u32_u24_e32 v5, 0x2c00, v5
	v_lshl_add_u64 v[28:29], s[26:27], 0, v[2:3]
	v_lshlrev_b32_e32 v30, 2, v5
	v_mov_b32_e32 v31, v3
	v_lshl_add_u64 v[56:57], v[28:29], 0, v[30:31]
	s_mov_b32 s26, 0x58000
	v_add_co_u32_e32 v32, vcc, s26, v56
	s_mov_b32 s26, 0xb0000
	s_nop 0
	v_addc_co_u32_e32 v33, vcc, 0, v57, vcc
	v_add_co_u32_e32 v36, vcc, s26, v56
	s_mov_b32 s26, 0x108000
	s_nop 0
	v_addc_co_u32_e32 v37, vcc, 0, v57, vcc
	v_add_co_u32_e32 v40, vcc, s26, v56
	s_mov_b32 s26, 0x160000
	s_nop 0
	v_addc_co_u32_e32 v41, vcc, 0, v57, vcc
	v_add_co_u32_e32 v44, vcc, s26, v56
	s_mov_b32 s26, 0x1b8000
	s_nop 0
	v_addc_co_u32_e32 v45, vcc, 0, v57, vcc
	v_add_co_u32_e32 v48, vcc, s26, v56
	global_load_dwordx4 v[28:31], v[56:57], off
	s_nop 0
	global_load_dwordx4 v[32:35], v[32:33], off
	v_addc_co_u32_e32 v49, vcc, 0, v57, vcc
	global_load_dwordx4 v[36:39], v[36:37], off
	s_nop 0
	global_load_dwordx4 v[40:43], v[40:41], off
	s_nop 0
	global_load_dwordx4 v[44:47], v[44:45], off
	s_nop 0
	global_load_dwordx4 v[48:51], v[48:49], off
	s_mov_b32 s26, 0x210000
	v_add_co_u32_e32 v52, vcc, s26, v56
	s_mov_b32 s26, 0x268000
	s_nop 0
	v_addc_co_u32_e32 v53, vcc, 0, v57, vcc
	global_load_dwordx4 v[52:55], v[52:53], off
	v_add_co_u32_e32 v56, vcc, s26, v56
	s_lshl_b32 s12, s12, 2
	s_nop 0
	v_addc_co_u32_e32 v57, vcc, 0, v57, vcc
	global_load_dwordx4 v[56:59], v[56:57], off
	s_and_b32 s12, s12, 0x7e0
	s_add_i32 s12, s12, s13
	s_lshl_b32 s12, s12, 15
	s_add_u32 s26, s37, s12
	s_addc_u32 s27, s36, 0
	v_mov_b32_e32 v5, v3
	s_waitcnt vmcnt(7)
	ds_write2_b32 v12, v28, v29 offset1:1
	ds_write2_b32 v12, v30, v31 offset0:2 offset1:3
	s_waitcnt vmcnt(6)
	ds_write2_b32 v13, v32, v33 offset1:1
	ds_write2_b32 v14, v34, v35 offset1:1
	s_waitcnt vmcnt(5)
	ds_write2_b32 v15, v36, v37 offset1:1
	ds_write2_b32 v16, v38, v39 offset1:1
	s_waitcnt vmcnt(4)
	ds_write2_b32 v17, v40, v41 offset1:1
	ds_write2_b32 v18, v42, v43 offset1:1
	s_waitcnt vmcnt(3)
	ds_write2_b32 v19, v44, v45 offset1:1
	ds_write2_b32 v20, v46, v47 offset1:1
	s_waitcnt vmcnt(2)
	ds_write2_b32 v21, v48, v49 offset1:1
	ds_write2_b32 v22, v50, v51 offset1:1
	s_waitcnt vmcnt(1)
	ds_write2_b32 v23, v52, v53 offset1:1
	ds_write2_b32 v24, v54, v55 offset1:1
	s_waitcnt vmcnt(0)
	ds_write2_b32 v25, v56, v57 offset1:1
	ds_write2_b32 v27, v58, v59 offset1:1
	s_waitcnt lgkmcnt(0)
	v_or_b32_e32 v32, s24, v6
	ds_read2_b32 v[60:61], v10 offset1:33
	ds_read2_b32 v[62:63], v10 offset0:66 offset1:99
	ds_read2_b32 v[64:65], v10 offset0:132 offset1:165
	ds_read2_b32 v[66:67], v10 offset0:198 offset1:231
	ds_read2_b32 v[68:69], v10 offset0:8 offset1:41
	ds_read2_b32 v[70:71], v10 offset0:74 offset1:107
	ds_read2_b32 v[72:73], v10 offset0:140 offset1:173
	ds_read2_b32 v[74:75], v10 offset0:206 offset1:239
	ds_read2_b32 v[76:77], v10 offset0:16 offset1:49
	ds_read2_b32 v[78:79], v10 offset0:82 offset1:115
	ds_read2_b32 v[80:81], v10 offset0:148 offset1:181
	ds_read2_b32 v[82:83], v10 offset0:214 offset1:247
	ds_read2_b32 v[84:85], v10 offset0:24 offset1:57
	ds_read2_b32 v[86:87], v10 offset0:90 offset1:123
	ds_read2_b32 v[88:89], v10 offset0:156 offset1:189
	ds_read2_b32 v[90:91], v10 offset0:222 offset1:255
	v_lshlrev_b32_e32 v32, 7, v32
	s_waitcnt lgkmcnt(15)
	v_cvt_pk_bf16_f32 v28, v60, v61
	v_mov_b32_e32 v33, v3
	v_and_b32_e32 v32, 0x7380, v32
	s_waitcnt lgkmcnt(14)
	v_cvt_pk_bf16_f32 v29, v62, v63
	v_lshl_add_u64 v[32:33], s[26:27], 0, v[32:33]
	s_waitcnt lgkmcnt(13)
	v_cvt_pk_bf16_f32 v30, v64, v65
	s_waitcnt lgkmcnt(12)
	v_cvt_pk_bf16_f32 v31, v66, v67
	v_lshl_add_u64 v[32:33], v[32:33], 0, v[4:5]
	global_store_dwordx4 v[32:33], v[28:31], off
	s_waitcnt lgkmcnt(11)
	s_nop 0
	v_cvt_pk_bf16_f32 v28, v68, v69
	s_waitcnt lgkmcnt(10)
	v_cvt_pk_bf16_f32 v29, v70, v71
	s_waitcnt lgkmcnt(9)
	v_cvt_pk_bf16_f32 v30, v72, v73
	v_or_b32_e32 v31, s24, v7
	v_lshlrev_b32_e32 v34, 7, v31
	v_mov_b32_e32 v35, v3
	v_and_b32_e32 v34, 0x7780, v34
	v_lshl_add_u64 v[34:35], s[26:27], 0, v[34:35]
	s_waitcnt lgkmcnt(8)
	v_cvt_pk_bf16_f32 v31, v74, v75
	v_lshl_add_u64 v[34:35], v[34:35], 0, v[4:5]
	global_store_dwordx4 v[34:35], v[28:31], off
	v_mov_b32_e32 v35, v3
	s_waitcnt lgkmcnt(7)
	v_cvt_pk_bf16_f32 v28, v76, v77
	s_waitcnt lgkmcnt(6)
	v_cvt_pk_bf16_f32 v29, v78, v79
	s_waitcnt lgkmcnt(5)
	v_cvt_pk_bf16_f32 v30, v80, v81
	v_or_b32_e32 v31, s24, v8
	v_lshlrev_b32_e32 v34, 7, v31
	v_and_b32_e32 v34, 0x7b80, v34
	v_lshl_add_u64 v[34:35], s[26:27], 0, v[34:35]
	s_waitcnt lgkmcnt(4)
	v_cvt_pk_bf16_f32 v31, v82, v83
	v_lshl_add_u64 v[34:35], v[34:35], 0, v[4:5]
	global_store_dwordx4 v[34:35], v[28:31], off
	s_waitcnt lgkmcnt(3)
	s_nop 0
	v_cvt_pk_bf16_f32 v28, v84, v85
	s_waitcnt lgkmcnt(2)
	v_cvt_pk_bf16_f32 v29, v86, v87
	s_waitcnt lgkmcnt(1)
	v_cvt_pk_bf16_f32 v30, v88, v89
	v_or_b32_e32 v31, s24, v9
	v_lshlrev_b32_e32 v31, 7, v31
	v_mov_b32_e32 v33, v3
	v_and_b32_e32 v32, 0x7f80, v31
	v_lshl_add_u64 v[32:33], s[26:27], 0, v[32:33]
	v_lshl_add_u64 v[32:33], v[32:33], 0, v[4:5]
	s_waitcnt lgkmcnt(0)
	v_cvt_pk_bf16_f32 v31, v90, v91
	global_store_dwordx4 v[32:33], v[28:31], off
	s_waitcnt lgkmcnt(0)

.LBB0_22:
	s_andn2_b64 vcc, exec, s[26:27]
	s_cbranch_vccnz .LBB0_24
	s_load_dwordx2 s[26:27], s[22:23], 0x80
	s_and_b32 s12, s11, 0x1fc0
	s_mul_i32 s24, s10, 0x1400000
	s_addk_i32 s12, 0xf000
	s_mul_hi_i32 s13, s10, 0x1400000
	s_waitcnt lgkmcnt(0)
	s_add_u32 s24, s26, s24
	s_addc_u32 s13, s27, s13
	s_and_b32 s26, s33, 0x7e0
	s_mul_i32 s36, s10, 0xa00000
	s_mul_hi_i32 s27, s10, 0xa00000
	s_add_u32 s36, s19, s36
	s_addc_u32 s37, s28, s27
	s_lshl_b32 s26, s26, 2
	v_or_b32_e32 v56, s12, v6
	s_add_u32 s26, s24, s26
	s_addc_u32 s27, s13, 0
	v_mov_b32_e32 v57, v3
	v_or_b32_e32 v30, 8, v56
	v_mov_b32_e32 v31, v3
	v_or_b32_e32 v36, 16, v56
	v_mov_b32_e32 v37, v3
	v_or_b32_e32 v38, 24, v56
	v_mov_b32_e32 v39, v3
	v_or_b32_e32 v44, 32, v56
	v_mov_b32_e32 v45, v3
	v_or_b32_e32 v46, 40, v56
	v_mov_b32_e32 v47, v3
	v_lshl_add_u64 v[58:59], s[26:27], 0, v[2:3]
	v_lshlrev_b64 v[28:29], 13, v[56:57]
	v_lshlrev_b64 v[30:31], 13, v[30:31]
	v_lshlrev_b64 v[36:37], 13, v[36:37]
	v_lshlrev_b64 v[38:39], 13, v[38:39]
	v_lshlrev_b64 v[44:45], 13, v[44:45]
	v_lshlrev_b64 v[46:47], 13, v[46:47]
	v_lshl_add_u64 v[28:29], v[58:59], 0, v[28:29]
	v_lshl_add_u64 v[32:33], v[58:59], 0, v[30:31]
	v_lshl_add_u64 v[36:37], v[58:59], 0, v[36:37]
	v_lshl_add_u64 v[40:41], v[58:59], 0, v[38:39]
	v_lshl_add_u64 v[44:45], v[58:59], 0, v[44:45]
	v_lshl_add_u64 v[48:49], v[58:59], 0, v[46:47]
	global_load_dwordx4 v[28:31], v[28:29], off
	s_nop 0
	global_load_dwordx4 v[32:35], v[32:33], off
	s_nop 0
	global_load_dwordx4 v[36:39], v[36:37], off
	s_nop 0
	global_load_dwordx4 v[40:43], v[40:41], off
	s_nop 0
	global_load_dwordx4 v[44:47], v[44:45], off
	s_nop 0
	global_load_dwordx4 v[48:51], v[48:49], off
	v_or_b32_e32 v52, 48, v56
	v_mov_b32_e32 v53, v3
	v_lshlrev_b64 v[52:53], 13, v[52:53]
	v_lshl_add_u64 v[52:53], v[58:59], 0, v[52:53]
	v_or_b32_e32 v56, 56, v56
	global_load_dwordx4 v[52:55], v[52:53], off
	v_lshlrev_b64 v[56:57], 13, v[56:57]
	v_lshl_add_u64 v[56:57], v[58:59], 0, v[56:57]
	global_load_dwordx4 v[56:59], v[56:57], off
	s_mul_i32 s13, s10, 0xfd200000
	s_lshr_b32 s12, s12, 6
	v_mov_b32_e32 v5, v3
	s_waitcnt vmcnt(7)
	ds_write2_b32 v12, v28, v29 offset1:1
	ds_write2_b32 v12, v30, v31 offset0:2 offset1:3
	s_waitcnt vmcnt(6)
	ds_write2_b32 v13, v32, v33 offset1:1
	ds_write2_b32 v14, v34, v35 offset1:1
	s_waitcnt vmcnt(5)
	ds_write2_b32 v15, v36, v37 offset1:1
	ds_write2_b32 v16, v38, v39 offset1:1
	s_waitcnt vmcnt(4)
	ds_write2_b32 v17, v40, v41 offset1:1
	ds_write2_b32 v18, v42, v43 offset1:1
	s_waitcnt vmcnt(3)
	ds_write2_b32 v19, v44, v45 offset1:1
	ds_write2_b32 v20, v46, v47 offset1:1
	s_waitcnt vmcnt(2)
	ds_write2_b32 v21, v48, v49 offset1:1
	ds_write2_b32 v22, v50, v51 offset1:1
	s_waitcnt vmcnt(1)
	ds_write2_b32 v23, v52, v53 offset1:1
	ds_write2_b32 v24, v54, v55 offset1:1
	s_waitcnt vmcnt(0)
	ds_write2_b32 v25, v56, v57 offset1:1
	ds_write2_b32 v27, v58, v59 offset1:1
	v_add_u32_e32 v36, s13, v11
	s_bfe_u32 s13, s33, 0x30008
	s_mul_i32 s13, s13, 40
	s_waitcnt lgkmcnt(0)
	s_add_i32 s24, s13, s12
	s_lshl_b64 s[26:27], s[24:25], 15
	ds_read2_b32 v[60:61], v10 offset1:33
	ds_read2_b32 v[62:63], v10 offset0:66 offset1:99
	ds_read2_b32 v[64:65], v10 offset0:132 offset1:165
	ds_read2_b32 v[66:67], v10 offset0:198 offset1:231
	ds_read2_b32 v[68:69], v10 offset0:8 offset1:41
	ds_read2_b32 v[70:71], v10 offset0:74 offset1:107
	ds_read2_b32 v[72:73], v10 offset0:140 offset1:173
	ds_read2_b32 v[74:75], v10 offset0:206 offset1:239
	ds_read2_b32 v[76:77], v10 offset0:16 offset1:49
	ds_read2_b32 v[78:79], v10 offset0:82 offset1:115
	ds_read2_b32 v[80:81], v10 offset0:148 offset1:181
	ds_read2_b32 v[82:83], v10 offset0:214 offset1:247
	ds_read2_b32 v[84:85], v10 offset0:24 offset1:57
	ds_read2_b32 v[86:87], v10 offset0:90 offset1:123
	ds_read2_b32 v[88:89], v10 offset0:156 offset1:189
	ds_read2_b32 v[90:91], v10 offset0:222 offset1:255
	v_and_b32_e32 v32, 0x39c0, v36
	s_add_u32 s26, s36, s26
	s_waitcnt lgkmcnt(15)
	v_cvt_pk_bf16_f32 v28, v60, v61
	v_mov_b32_e32 v33, v3
	v_lshlrev_b32_e32 v32, 1, v32
	s_addc_u32 s27, s37, s27
	s_waitcnt lgkmcnt(14)
	v_cvt_pk_bf16_f32 v29, v62, v63
	v_lshl_add_u64 v[32:33], s[26:27], 0, v[32:33]
	s_waitcnt lgkmcnt(13)
	v_cvt_pk_bf16_f32 v30, v64, v65
	s_waitcnt lgkmcnt(12)
	v_cvt_pk_bf16_f32 v31, v66, v67
	v_lshl_add_u64 v[32:33], v[32:33], 0, v[4:5]
	global_store_dwordx4 v[32:33], v[28:31], off
	s_waitcnt lgkmcnt(11)
	s_nop 0
	v_cvt_pk_bf16_f32 v28, v68, v69
	s_waitcnt lgkmcnt(10)
	v_cvt_pk_bf16_f32 v29, v70, v71
	s_waitcnt lgkmcnt(9)
	v_cvt_pk_bf16_f32 v30, v72, v73
	v_add_u32_e32 v31, 0x200, v36
	v_and_b32_e32 v34, 0x3bc0, v31
	v_mov_b32_e32 v35, v3
	v_lshlrev_b32_e32 v34, 1, v34
	v_lshl_add_u64 v[34:35], s[26:27], 0, v[34:35]
	s_waitcnt lgkmcnt(8)
	v_cvt_pk_bf16_f32 v31, v74, v75
	v_lshl_add_u64 v[34:35], v[34:35], 0, v[4:5]
	global_store_dwordx4 v[34:35], v[28:31], off
	v_mov_b32_e32 v35, v3
	s_waitcnt lgkmcnt(7)
	v_cvt_pk_bf16_f32 v28, v76, v77
	s_waitcnt lgkmcnt(6)
	v_cvt_pk_bf16_f32 v29, v78, v79
	s_waitcnt lgkmcnt(5)
	v_cvt_pk_bf16_f32 v30, v80, v81
	v_add_u32_e32 v31, 0x400, v36
	v_and_b32_e32 v34, 0x3dc0, v31
	v_lshlrev_b32_e32 v34, 1, v34
	v_lshl_add_u64 v[34:35], s[26:27], 0, v[34:35]
	s_waitcnt lgkmcnt(4)
	v_cvt_pk_bf16_f32 v31, v82, v83
	v_lshl_add_u64 v[34:35], v[34:35], 0, v[4:5]
	global_store_dwordx4 v[34:35], v[28:31], off
	s_waitcnt lgkmcnt(3)
	s_nop 0
	v_cvt_pk_bf16_f32 v28, v84, v85
	s_waitcnt lgkmcnt(2)
	v_cvt_pk_bf16_f32 v29, v86, v87
	s_waitcnt lgkmcnt(1)
	v_cvt_pk_bf16_f32 v30, v88, v89
	v_add_u32_e32 v31, 0x600, v36
	v_and_b32_e32 v31, 0x3fc0, v31
	v_mov_b32_e32 v33, v3
	v_lshlrev_b32_e32 v32, 1, v31
	v_lshl_add_u64 v[32:33], s[26:27], 0, v[32:33]
	v_lshl_add_u64 v[32:33], v[32:33], 0, v[4:5]
	s_waitcnt lgkmcnt(0)
	v_cvt_pk_bf16_f32 v31, v90, v91
	global_store_dwordx4 v[32:33], v[28:31], off
	s_waitcnt lgkmcnt(0)

.LBB0_25:
	s_andn2_b64 vcc, exec, s[26:27]
	s_cbranch_vccnz .LBB0_14
	s_bfe_u32 s12, s11, 0x70018
	s_add_i32 s12, s11, s12
	s_sext_i32_i16 s13, s12
	s_and_b32 s12, s12, 0xff80
	s_sub_i32 s11, s11, s12
	s_sext_i32_i16 s11, s11
	s_load_dwordx2 s[26:27], s[22:23], 0x40
	s_lshl_b32 s12, s11, 5
	s_lshr_b32 s24, s13, 7
	s_ashr_i32 s13, s13, 7
	s_add_i32 s36, s12, 0x200
	s_add_i32 s37, s12, 0x400
	s_cmp_lt_i32 s11, 48
	s_cselect_b32 s11, s12, s37
	s_mul_i32 s37, s10, 0x2400000
	s_cselect_b32 s36, s12, s36
	s_mul_hi_i32 s12, s10, 0x2400000
	s_waitcnt lgkmcnt(0)
	s_add_u32 s38, s26, s37
	s_addc_u32 s12, s27, s12
	s_mul_hi_i32 s26, s10, 0x1400000
	s_mul_i32 s10, s10, 0x1400000
	s_add_u32 s10, s29, s10
	s_addc_u32 s39, s30, s26
	s_ashr_i32 s37, s36, 31
	s_lshl_b64 s[26:27], s[36:37], 2
	v_lshl_or_b32 v5, s13, 6, v6
	s_add_u32 s26, s38, s26
	s_addc_u32 s27, s12, s27
	v_mul_i32_i24_e32 v30, 0x1200, v5
	v_lshl_add_u64 v[28:29], s[26:27], 0, v[2:3]
	v_ashrrev_i32_e32 v31, 31, v30
	v_lshl_add_u64 v[56:57], v[30:31], 2, v[28:29]
	s_mov_b32 s12, 0x24000
	v_add_co_u32_e32 v32, vcc, s12, v56
	s_mov_b32 s12, 0x48000
	s_nop 0
	v_addc_co_u32_e32 v33, vcc, 0, v57, vcc
	v_add_co_u32_e32 v36, vcc, s12, v56
	s_mov_b32 s12, 0x6c000
	s_nop 0
	v_addc_co_u32_e32 v37, vcc, 0, v57, vcc
	v_add_co_u32_e32 v40, vcc, s12, v56
	s_mov_b32 s12, 0x90000
	s_nop 0
	v_addc_co_u32_e32 v41, vcc, 0, v57, vcc
	v_add_co_u32_e32 v44, vcc, s12, v56
	s_mov_b32 s12, 0xb4000
	s_nop 0
	v_addc_co_u32_e32 v45, vcc, 0, v57, vcc
	v_add_co_u32_e32 v48, vcc, s12, v56
	global_load_dwordx4 v[28:31], v[56:57], off
	s_nop 0
	global_load_dwordx4 v[32:35], v[32:33], off
	v_addc_co_u32_e32 v49, vcc, 0, v57, vcc
	global_load_dwordx4 v[36:39], v[36:37], off
	s_nop 0
	global_load_dwordx4 v[40:43], v[40:41], off
	s_nop 0
	global_load_dwordx4 v[44:47], v[44:45], off
	s_nop 0
	global_load_dwordx4 v[48:51], v[48:49], off
	s_mov_b32 s12, 0xd8000
	v_add_co_u32_e32 v52, vcc, s12, v56
	s_mov_b32 s12, 0xfc000
	s_nop 0
	v_addc_co_u32_e32 v53, vcc, 0, v57, vcc
	global_load_dwordx4 v[52:55], v[52:53], off
	v_add_co_u32_e32 v56, vcc, s12, v56
	s_ashr_i32 s36, s11, 8
	s_nop 0
	v_addc_co_u32_e32 v57, vcc, 0, v57, vcc
	global_load_dwordx4 v[56:59], v[56:57], off
	s_bfe_i64 s[26:27], s[24:25], 0x100000
	s_ashr_i32 s37, s36, 31
	s_lshl_b64 s[26:27], s[26:27], 15
	s_lshl_b64 s[36:37], s[36:37], 20
	s_add_u32 s10, s10, s36
	s_addc_u32 s12, s39, s37
	s_add_u32 s26, s10, s26
	s_addc_u32 s27, s12, s27
	v_mov_b32_e32 v5, v3
	s_waitcnt vmcnt(7)
	ds_write2_b32 v12, v28, v29 offset1:1
	ds_write2_b32 v12, v30, v31 offset0:2 offset1:3
	s_waitcnt vmcnt(6)
	ds_write2_b32 v13, v32, v33 offset1:1
	ds_write2_b32 v14, v34, v35 offset1:1
	s_waitcnt vmcnt(5)
	ds_write2_b32 v15, v36, v37 offset1:1
	ds_write2_b32 v16, v38, v39 offset1:1
	s_waitcnt vmcnt(4)
	ds_write2_b32 v17, v40, v41 offset1:1
	ds_write2_b32 v18, v42, v43 offset1:1
	s_waitcnt vmcnt(3)
	ds_write2_b32 v19, v44, v45 offset1:1
	ds_write2_b32 v20, v46, v47 offset1:1
	s_waitcnt vmcnt(2)
	ds_write2_b32 v21, v48, v49 offset1:1
	ds_write2_b32 v22, v50, v51 offset1:1
	s_waitcnt vmcnt(1)
	ds_write2_b32 v23, v52, v53 offset1:1
	ds_write2_b32 v24, v54, v55 offset1:1
	s_waitcnt vmcnt(0)
	ds_write2_b32 v25, v56, v57 offset1:1
	ds_write2_b32 v27, v58, v59 offset1:1
	s_waitcnt lgkmcnt(0)
	ds_read2_b32 v[60:61], v10 offset1:33
	ds_read2_b32 v[62:63], v10 offset0:66 offset1:99
	ds_read2_b32 v[64:65], v10 offset0:132 offset1:165
	ds_read2_b32 v[66:67], v10 offset0:198 offset1:231
	ds_read2_b32 v[68:69], v10 offset0:8 offset1:41
	ds_read2_b32 v[70:71], v10 offset0:74 offset1:107
	ds_read2_b32 v[72:73], v10 offset0:140 offset1:173
	ds_read2_b32 v[74:75], v10 offset0:206 offset1:239
	ds_read2_b32 v[76:77], v10 offset0:16 offset1:49
	ds_read2_b32 v[78:79], v10 offset0:82 offset1:115
	ds_read2_b32 v[80:81], v10 offset0:148 offset1:181
	ds_read2_b32 v[82:83], v10 offset0:214 offset1:247
	ds_read2_b32 v[84:85], v10 offset0:24 offset1:57
	ds_read2_b32 v[86:87], v10 offset0:90 offset1:123
	ds_read2_b32 v[88:89], v10 offset0:156 offset1:189
	ds_read2_b32 v[90:91], v10 offset0:222 offset1:255
	s_waitcnt lgkmcnt(15)
	v_cvt_pk_bf16_f32 v28, v60, v61
	v_or_b32_e32 v29, s11, v6
	v_lshlrev_b32_e32 v29, 7, v29
	v_mov_b32_e32 v33, v3
	v_and_b32_e32 v32, 0x7380, v29
	s_waitcnt lgkmcnt(14)
	v_cvt_pk_bf16_f32 v29, v62, v63
	v_lshl_add_u64 v[32:33], s[26:27], 0, v[32:33]
	s_waitcnt lgkmcnt(13)
	v_cvt_pk_bf16_f32 v30, v64, v65
	s_waitcnt lgkmcnt(12)
	v_cvt_pk_bf16_f32 v31, v66, v67
	v_lshl_add_u64 v[32:33], v[32:33], 0, v[4:5]
	global_store_dwordx4 v[32:33], v[28:31], off
	s_waitcnt lgkmcnt(11)
	s_nop 0
	v_cvt_pk_bf16_f32 v28, v68, v69
	s_waitcnt lgkmcnt(10)
	v_cvt_pk_bf16_f32 v29, v70, v71
	s_waitcnt lgkmcnt(9)
	v_cvt_pk_bf16_f32 v30, v72, v73
	v_or_b32_e32 v31, s11, v7
	v_lshlrev_b32_e32 v34, 7, v31
	v_mov_b32_e32 v35, v3
	v_and_b32_e32 v34, 0x7780, v34
	v_lshl_add_u64 v[34:35], s[26:27], 0, v[34:35]
	s_waitcnt lgkmcnt(8)
	v_cvt_pk_bf16_f32 v31, v74, v75
	v_lshl_add_u64 v[34:35], v[34:35], 0, v[4:5]
	global_store_dwordx4 v[34:35], v[28:31], off
	v_mov_b32_e32 v35, v3
	s_waitcnt lgkmcnt(7)
	v_cvt_pk_bf16_f32 v28, v76, v77
	s_waitcnt lgkmcnt(6)
	v_cvt_pk_bf16_f32 v29, v78, v79
	s_waitcnt lgkmcnt(5)
	v_cvt_pk_bf16_f32 v30, v80, v81
	v_or_b32_e32 v31, s11, v8
	v_lshlrev_b32_e32 v34, 7, v31
	v_and_b32_e32 v34, 0x7b80, v34
	v_lshl_add_u64 v[34:35], s[26:27], 0, v[34:35]
	s_waitcnt lgkmcnt(4)
	v_cvt_pk_bf16_f32 v31, v82, v83
	v_lshl_add_u64 v[34:35], v[34:35], 0, v[4:5]
	global_store_dwordx4 v[34:35], v[28:31], off
	s_waitcnt lgkmcnt(3)
	s_nop 0
	v_cvt_pk_bf16_f32 v28, v84, v85
	s_waitcnt lgkmcnt(2)
	v_cvt_pk_bf16_f32 v29, v86, v87
	s_waitcnt lgkmcnt(1)
	v_cvt_pk_bf16_f32 v30, v88, v89
	v_or_b32_e32 v31, s11, v9
	v_lshlrev_b32_e32 v31, 7, v31
	v_mov_b32_e32 v33, v3
	v_and_b32_e32 v32, 0x7f80, v31
	v_lshl_add_u64 v[32:33], s[26:27], 0, v[32:33]
	v_lshl_add_u64 v[32:33], v[32:33], 0, v[4:5]
	s_waitcnt lgkmcnt(0)
	v_cvt_pk_bf16_f32 v31, v90, v91
	global_store_dwordx4 v[32:33], v[28:31], off
	s_waitcnt lgkmcnt(0)
	s_branch .LBB0_14
